# attnB loop: 4-deep LDS ring, coalesced swizzled K image, buffer-form LDS-DMA with SGPR tile offset
# speedup vs baseline: 1.0097x; 1.0097x over previous
; #define B_DMA(t, boff) do { const size_t go = (size_t)(((t) + rot) & 63) * 64 * 512; \
;         GLDS16(kg + go, kd + (boff)); GLDS16(kg + go + 64, kd + BK_IMG + (boff)); GLDS16(vg0 + go, vd0 + (boff)); GLDS16(vg0 + go + 64, vd0 + 2 * BV_DB + (boff)); } while (0)
; #define B_WAITBAR() do { asm volatile("s_waitcnt vmcnt(0)" ::: "memory"); __syncthreads(); } while (0)
; #define B_QK(boff, S0, S1) do { const LAS unsigned char* kb_ = lds + (boff) + koff; _Pragma("unroll") for (int ks = 0; ks < 4; ++ks) { \
;         const bf16x8 a0 = *(const LAS bf16x8*)(kb_ + 2 * ks * BK_CH), a1 = *(const LAS bf16x8*)(kb_ + 2 * ks * BK_CH + 512); \
;         S0 = MFMA32(a0, qf[ks], S0); S1 = MFMA32(a1, qf[ks], S1); } } while (0)
; __device__ __forceinline__ void attnB_unit(LAS unsigned char* lds, const unsigned char* ws, int unit, float lam, const float* subln_g) {
;     const int tid = threadIdx.x, lane = tid & 63, wid = __builtin_amdgcn_readfirstlane(tid >> 6), w = wid & 3, c = wid >> 2, r = lane & 31, h = lane >> 5;
;     const int qb = unit & 31, hd = (unit >> 5) & 3, b = unit >> 7, q0 = qb * 128;
;     const bf16* QB = (const bf16*)(ws + WS_QB); const bf16* KB = (const bf16*)(ws + WS_KB); const bf16* VB = (const bf16*)(ws + WS_VB); bf16* OB = (bf16*)(ws + WS_ATTA);
;     const size_t rowb = (size_t)b * SEQ;
;     const size_t qrow = rowb + q0 + 32 * w + r;
;     bf16x8 qf[4];
; #pragma unroll
;     for (int ks = 0; ks < 4; ++ks) qf[ks] = *(const bf16x8*)(QB + qrow * 512 + hd * 128 + c * 64 + 16 * ks + 8 * h);
;     const int rot = (qb * 2) & 63;
;     const bf16* kg = KB + (rowb + lane) * 512 + hd * 128 + wid * 8;
;     const bf16* vg0 = VB + (rowb + (wid & 3) * 16 + (lane >> 2)) * 512 + hd * 128 + (wid >> 2) * 32 + (lane & 3) * 8;
;     const unsigned ldsb = (unsigned)(unsigned long)lds;
;     const unsigned kd = ldsb + wid * BK_CH, vd0 = ldsb + 2 * BK_IMG + (wid >> 2) * BV_DB + (wid & 3) * 1024;
;     ...
;     const int i16 = lane & 15, qd = i16 >> 2, pp = i16 & 3, blk = (lane >> 4) & 1;
;     const int voff = 2 * BK_IMG + (4 * h + qd) * 64 + blk * 32 + pp * 8, koff = c * BK_IMG + h * BK_CH + r * 16;
;     constexpr int NT = SEQ / 64;
;     B_DMA(0, 0); B_DMA(1, BBUF);
;     B_WAITBAR();
;     f32x16 n0 = {}, n1 = {};
;     B_QK(0, n0, n1);
.LBB0_294:
	v_readfirstlane_b32 s38, v160
	s_bfe_u32 s39, s38, 0x20006
	s_and_b32 s10, s78, 31
	s_ashr_i32 s0, s78, 7
	s_lshl_b32 s4, s10, 7
	s_lshl_b32 s6, s39, 5
	s_ashr_i32 s1, s0, 31
	s_or_b32 s4, s6, s4
	s_lshl_b64 s[0:1], s[0:1], 12
	v_or_b32_e32 v0, s4, v161
	v_or_b32_e32 v172, s0, v0
	v_mov_b32_e32 v173, s1
	s_lshl_b32 s4, s78, 2
	v_lshlrev_b64 v[0:1], 10, v[172:173]
	s_and_b32 s37, s4, 0x180
	s_lshr_b32 s40, s38, 8
	v_lshl_add_u64 v[0:1], s[22:23], 0, v[0:1]
	s_lshl_b32 s4, s37, 1
	v_lshl_add_u64 v[0:1], v[0:1], 0, s[4:5]
	s_lshl_b32 s6, s40, 7
	s_mov_b32 s7, s5
	v_lshl_add_u64 v[0:1], v[0:1], 0, s[6:7]
	v_lshl_add_u64 v[0:1], v[0:1], 0, v[166:167]
	global_load_dwordx4 v[128:131], v[0:1], off
	global_load_dwordx4 v[132:135], v[0:1], off offset:32
	global_load_dwordx4 v[136:139], v[0:1], off offset:64
	global_load_dwordx4 v[140:143], v[0:1], off offset:96
	s_lshr_b32 s8, s38, 6
	v_lshrrev_b32_e32 v2, 3, v164
	v_lshl_add_u32 v2, s8, 3, v2
	v_lshrrev_b32_e32 v3, 4, v164
	s_and_b32 s9, s8, 1
	s_lshl_b32 s9, s9, 2
	v_or_b32_e32 v3, s9, v3
	v_and_b32_e32 v4, 7, v164
	v_xor_b32_e32 v3, v3, v4
	v_lshlrev_b32_e32 v4, 4, v3
	v_mov_b32_e32 v5, 0
	v_mov_b32_e32 v1, s1
	v_or_b32_e32 v0, s0, v2
	v_lshlrev_b64 v[0:1], 10, v[0:1]
	s_lshr_b32 s11, s38, 6
	v_lshl_add_u64 v[0:1], s[24:25], 0, v[0:1]
	v_lshl_add_u64 v[0:1], v[0:1], 0, s[4:5]
	s_lshl_b32 s8, s11, 4
	s_mov_b32 s9, s5
	v_lshl_add_u64 v[174:175], v[0:1], 0, v[4:5]
	v_lshl_or_b32 v0, s39, 4, v165
	v_or_b32_e32 v0, s0, v0
	v_mov_b32_e32 v1, s1
	v_lshlrev_b64 v[0:1], 10, v[0:1]
	v_lshl_add_u64 v[0:1], s[26:27], 0, v[0:1]
	s_mul_i32 s0, s40, 0x1040
	s_lshl_b32 s6, s40, 6
	v_lshl_add_u64 v[0:1], v[0:1], 0, s[4:5]
	s_add_i32 s0, s0, 0
	s_lshl_b32 s1, s39, 10
	v_lshl_add_u64 v[0:1], v[0:1], 0, s[6:7]
	s_lshl_b32 s41, s11, 10
	s_add_i32 s49, s0, s1
	s_mul_i32 s0, s40, 0x2080
	s_lshl_b32 s4, s10, 17
	v_lshl_add_u64 v[176:177], v[0:1], 0, v[170:171]
	s_add_i32 s41, s41, 0
	v_add_u32_e32 v2, s0, v178
	v_lshl_add_u64 v[0:1], v[174:175], 0, s[4:5]
	s_mov_b32 s0, m0
	s_mov_b32 m0, s41
	s_nop 0
	global_load_lds_dwordx4 v[0:1], off
	s_mov_b32 m0, s0
	v_lshl_add_u64 v[0:1], v[0:1], 0, s[28:29]
	s_add_i32 s44, s41, 0x2080
	s_mov_b32 s0, m0
	s_mov_b32 m0, s44
	s_nop 0
	global_load_lds_dwordx4 v[0:1], off
	s_mov_b32 m0, s0
	s_add_i32 s43, s49, 0x4100
	v_lshl_add_u64 v[0:1], v[176:177], 0, s[4:5]
	s_mov_b32 s0, m0
	s_mov_b32 m0, s43
	s_nop 0
	global_load_lds_dwordx4 v[0:1], off
	s_mov_b32 m0, s0
	v_lshl_add_u64 v[0:1], v[0:1], 0, s[28:29]
	s_add_i32 s45, s49, 0x6180
	s_mov_b32 s0, m0
	s_mov_b32 m0, s45
	s_nop 0
	global_load_lds_dwordx4 v[0:1], off
	s_mov_b32 m0, s0
	s_bitset1_b32 s4, 16
	v_lshl_add_u64 v[0:1], v[174:175], 0, s[4:5]
	s_add_i32 s46, s41, 0x8200
	s_mov_b32 s0, m0
	s_mov_b32 m0, s46
	s_nop 0
	global_load_lds_dwordx4 v[0:1], off
	s_mov_b32 m0, s0
	v_lshl_add_u64 v[0:1], v[0:1], 0, s[28:29]
	s_add_i32 s47, s41, 0xa280
	s_mov_b32 s0, m0
	s_mov_b32 m0, s47
	s_nop 0
	global_load_lds_dwordx4 v[0:1], off
	s_mov_b32 m0, s0
	v_lshl_add_u64 v[0:1], v[176:177], 0, s[4:5]
	s_add_i32 s48, s49, 0xc300
	s_mov_b32 s0, m0
	s_mov_b32 m0, s48
	s_nop 0
	global_load_lds_dwordx4 v[0:1], off
	s_mov_b32 m0, s0
	v_lshl_add_u64 v[0:1], v[0:1], 0, s[28:29]
	s_add_i32 s49, s49, 0xe380
	s_mov_b32 s0, m0
	s_mov_b32 m0, s49
	s_nop 0
	global_load_lds_dwordx4 v[0:1], off
	s_mov_b32 m0, s0
	v_add_u32_e32 v190, 0, v2
	s_waitcnt vmcnt(0)
	s_barrier
	s_mul_i32 s0, s40, 0x2080
	v_lshlrev_b32_e32 v8, 7, v161
	v_add_u32_e32 v8, s0, v8
	v_bfe_u32 v9, v161, 1, 3
	v_bfe_u32 v10, v160, 5, 1
	v_or_b32_e32 v11, 0, v10
	v_xor_b32_e32 v11, v11, v9
	v_lshl_add_u32 v146, v11, 4, v8
	v_or_b32_e32 v11, 2, v10
	v_xor_b32_e32 v11, v11, v9
	v_lshl_add_u32 v147, v11, 4, v8
	v_or_b32_e32 v11, 4, v10
	v_xor_b32_e32 v11, v11, v9
	v_lshl_add_u32 v148, v11, 4, v8
	v_or_b32_e32 v11, 6, v10
	v_xor_b32_e32 v11, v11, v9
	v_lshl_add_u32 v149, v11, 4, v8
	ds_read_b128 v[0:3], v146
	ds_read_b128 v[4:7], v146 offset:4096
	ds_read_b128 v[32:35], v147
	ds_read_b128 v[36:39], v147 offset:4096
	v_cmp_lt_i32_e32 vcc, v186, v187
	s_mov_b32 s18, s5
	s_mov_b32 s19, s5
	s_mov_b32 s6, s5
	s_mov_b32 s8, s5
	s_mov_b32 s10, s5
	s_mov_b32 s11, s5
	s_mov_b32 s12, s5
	s_waitcnt vmcnt(3) lgkmcnt(3)
	v_mfma_f32_32x32x16_bf16 v[16:31], v[0:3], v[128:131], 0
	s_mov_b32 s13, s5
	s_mov_b32 s14, s5
	s_mov_b32 s15, s5
	s_mov_b32 s16, s5
	s_mov_b32 s4, s5
	s_mov_b32 s17, s5
	s_and_b32 s0, s36, 31
	s_waitcnt lgkmcnt(2)
	v_mfma_f32_32x32x16_bf16 v[0:15], v[4:7], v[128:131], 0
	s_lshl_b32 s0, s0, 16
	s_add_i32 s50, s0, 0x20000
	v_mov_b32_e32 v191, 0
	s_waitcnt vmcnt(2) lgkmcnt(1)
	v_mfma_f32_32x32x16_bf16 v[16:31], v[32:35], v[132:135], v[16:31]
	s_waitcnt lgkmcnt(0)
	v_mfma_f32_32x32x16_bf16 v[0:15], v[36:39], v[132:135], v[0:15]
	ds_read_b128 v[32:35], v148
	ds_read_b128 v[36:39], v148 offset:4096
	s_waitcnt vmcnt(1) lgkmcnt(1)
	v_mfma_f32_32x32x16_bf16 v[16:31], v[32:35], v[136:139], v[16:31]
	ds_read_b128 v[32:35], v149
	s_waitcnt lgkmcnt(1)
	v_mfma_f32_32x32x16_bf16 v[0:15], v[36:39], v[136:139], v[0:15]
	ds_read_b128 v[36:39], v149 offset:4096
	s_waitcnt vmcnt(0) lgkmcnt(1)
	v_mfma_f32_32x32x16_bf16 v[16:31], v[32:35], v[140:143], v[16:31]
	s_waitcnt lgkmcnt(0)
; __device__ __forceinline__ float xhalf(float v) { return __shfl_xor(v, 32); }
; __device__ __forceinline__ void attnB_unit(LAS unsigned char* lds, const unsigned char* ws, int unit, float lam, const float* subln_g) {
;     ...
;     float mrow = fmaxf(n0[0], n1[0]);
; #pragma unroll
;     for (int i = 1; i < 16; ++i) mrow = fmaxf(mrow, fmaxf(n0[i], n1[i]));
;     mrow = fmaxf(mrow, xhalf(mrow));
;     f32x16 negm;
; #pragma unroll
;     for (int i = 0; i < 16; ++i) { negm[i] = -mrow; n0[i] -= mrow; n1[i] -= mrow; }
;     f32x16 o[4] = {}; float l = 0.f;
	v_mfma_f32_32x32x16_bf16 v[0:15], v[36:39], v[140:143], v[0:15]
	s_nop 9
	v_max_f32_e32 v33, v17, v17
	v_max_f32_e32 v35, v18, v18
	v_max_f32_e32 v37, v19, v19
	v_max_f32_e32 v32, v1, v1
	v_max_f32_e32 v34, v2, v2
	v_max_f32_e32 v36, v3, v3
	v_max_f32_e32 v32, v33, v32
	v_max_f32_e32 v33, v35, v34
	v_max_f32_e32 v34, v37, v36
	v_max3_f32 v32, v16, v0, v32
	v_max_f32_e32 v38, v4, v4
	v_max3_f32 v32, v32, v33, v34
	v_max_f32_e32 v33, v20, v20
	v_max_f32_e32 v34, v5, v5
	v_max_f32_e32 v35, v21, v21
	v_max_f32_e32 v33, v33, v38
	v_max_f32_e32 v34, v35, v34
	v_max3_f32 v32, v32, v33, v34
	v_max_f32_e32 v33, v6, v6
	v_max_f32_e32 v34, v22, v22
	v_max_f32_e32 v33, v34, v33
	v_max_f32_e32 v34, v7, v7
	v_max_f32_e32 v35, v23, v23
	v_max_f32_e32 v34, v35, v34
	v_max3_f32 v32, v32, v33, v34
	v_max_f32_e32 v33, v8, v8
	v_max_f32_e32 v34, v24, v24
	v_max_f32_e32 v33, v34, v33
	v_max_f32_e32 v34, v9, v9
	v_max_f32_e32 v35, v25, v25
	v_max_f32_e32 v34, v35, v34
	v_max3_f32 v32, v32, v33, v34
	v_max_f32_e32 v33, v10, v10
	v_max_f32_e32 v34, v26, v26
	v_max_f32_e32 v33, v34, v33
	v_max_f32_e32 v34, v11, v11
	v_max_f32_e32 v35, v27, v27
	v_max_f32_e32 v34, v35, v34
	v_max3_f32 v32, v32, v33, v34
	v_max_f32_e32 v33, v12, v12
	v_max_f32_e32 v34, v28, v28
	v_max_f32_e32 v33, v34, v33
	v_max_f32_e32 v34, v13, v13
	v_max_f32_e32 v35, v29, v29
	v_max_f32_e32 v34, v35, v34
	v_max3_f32 v32, v32, v33, v34
	v_max_f32_e32 v33, v14, v14
	v_max_f32_e32 v34, v30, v30
	v_max_f32_e32 v33, v34, v33
	v_max_f32_e32 v34, v15, v15
	v_max_f32_e32 v35, v31, v31
	v_max_f32_e32 v34, v35, v34
	v_max3_f32 v48, v32, v33, v34
	v_cndmask_b32_e32 v32, v185, v186, vcc
	v_lshlrev_b32_e32 v189, 2, v32
	ds_bpermute_b32 v49, v189, v48
	v_mov_b64_e32 v[46:47], s[18:19]
	v_mov_b64_e32 v[32:33], s[4:5]
	v_mov_b64_e32 v[44:45], s[16:17]
	v_mov_b64_e32 v[42:43], s[14:15]
	s_waitcnt lgkmcnt(0)
	v_max_f32_e32 v49, v49, v49
	v_max_f32_e32 v48, v48, v49
	v_mov_b64_e32 v[40:41], s[12:13]
	v_mov_b64_e32 v[38:39], s[10:11]
	v_mov_b64_e32 v[36:37], s[8:9]
	v_mov_b64_e32 v[34:35], s[6:7]
	v_xor_b32_e32 v64, 0x80000000, v48
	v_sub_f32_e32 v127, v31, v48
	v_sub_f32_e32 v126, v30, v48
	v_sub_f32_e32 v125, v29, v48
	v_sub_f32_e32 v124, v28, v48
	v_sub_f32_e32 v123, v27, v48
	v_sub_f32_e32 v122, v26, v48
	v_sub_f32_e32 v121, v25, v48
	v_sub_f32_e32 v120, v24, v48
	v_sub_f32_e32 v119, v23, v48
	v_sub_f32_e32 v118, v22, v48
	v_sub_f32_e32 v117, v21, v48
	v_sub_f32_e32 v116, v20, v48
	v_sub_f32_e32 v115, v19, v48
	v_sub_f32_e32 v114, v18, v48
	v_sub_f32_e32 v113, v17, v48
	v_sub_f32_e32 v112, v16, v48
	v_sub_f32_e32 v95, v15, v48
	v_sub_f32_e32 v94, v14, v48
	v_sub_f32_e32 v93, v13, v48
	v_sub_f32_e32 v92, v12, v48
	v_sub_f32_e32 v91, v11, v48
	v_sub_f32_e32 v90, v10, v48
	v_sub_f32_e32 v89, v9, v48
	v_sub_f32_e32 v88, v8, v48
	v_sub_f32_e32 v87, v7, v48
	v_sub_f32_e32 v86, v6, v48
	v_sub_f32_e32 v85, v5, v48
	v_sub_f32_e32 v84, v4, v48
	v_sub_f32_e32 v83, v3, v48
	v_sub_f32_e32 v82, v2, v48
	v_sub_f32_e32 v81, v1, v48
	v_sub_f32_e32 v80, v0, v48
	v_mov_b64_e32 v[62:63], v[46:47]
	v_mov_b64_e32 v[16:17], v[32:33]
	v_mov_b64_e32 v[0:1], v[32:33]
	v_mov_b32_e32 v65, v64
	v_mov_b32_e32 v66, v64
	v_mov_b32_e32 v67, v64
	v_mov_b32_e32 v68, v64
	v_mov_b32_e32 v69, v64
	v_mov_b32_e32 v70, v64
	v_mov_b32_e32 v71, v64
	v_mov_b32_e32 v72, v64
	v_mov_b32_e32 v73, v64
	v_mov_b32_e32 v74, v64
	v_mov_b32_e32 v75, v64
	v_mov_b32_e32 v76, v64
	v_mov_b32_e32 v77, v64
	v_mov_b32_e32 v78, v64
	v_mov_b32_e32 v79, v64
	v_mov_b64_e32 v[60:61], v[44:45]
	v_mov_b64_e32 v[58:59], v[42:43]
	v_mov_b64_e32 v[56:57], v[40:41]
	v_mov_b64_e32 v[54:55], v[38:39]
	v_mov_b64_e32 v[52:53], v[36:37]
	v_mov_b64_e32 v[50:51], v[34:35]
	v_mov_b64_e32 v[48:49], v[32:33]
	v_mov_b64_e32 v[18:19], v[34:35]
	v_mov_b64_e32 v[20:21], v[36:37]
	v_mov_b64_e32 v[22:23], v[38:39]
	v_mov_b64_e32 v[24:25], v[40:41]
	v_mov_b64_e32 v[26:27], v[42:43]
	v_mov_b64_e32 v[28:29], v[44:45]
	v_mov_b64_e32 v[30:31], v[46:47]
	v_mov_b64_e32 v[2:3], v[34:35]
	v_mov_b64_e32 v[4:5], v[36:37]
	v_mov_b64_e32 v[6:7], v[38:39]
	v_mov_b64_e32 v[8:9], v[40:41]
	v_mov_b64_e32 v[10:11], v[42:43]
	v_mov_b64_e32 v[12:13], v[44:45]
	v_mov_b64_e32 v[14:15], v[46:47]
.LBB0_296:
	v_add_u32_e32 v150, 0x10400, v146
	v_add_u32_e32 v151, 0x10400, v147
	v_add_u32_e32 v152, 0x10400, v148
	v_add_u32_e32 v153, 0x10400, v149
	s_mov_b32 s8, s24
	s_and_b32 s9, s25, 0xffff
	s_mov_b32 s10, -1
	s_mov_b32 s11, 0x20000
	s_mov_b32 s12, s26
	s_and_b32 s13, s27, 0xffff
	s_mov_b32 s14, -1
	s_mov_b32 s15, 0x20000
	v_subrev_u32_e32 v250, s24, v174
	v_subrev_u32_e32 v251, s26, v176
	s_add_i32 s0, s50, 0xffff0000
	s_and_b32 s0, s0, 0x1f8000
	s_lshl_b32 s4, s0, 1
	s_add_i32 m0, s41, 0x10400
	s_nop 0
	buffer_load_dwordx4 v250, s[8:11], s4 offen lds
	s_add_i32 m0, s41, 0x12400
	s_nop 0
	buffer_load_dwordx4 v250, s[8:11], s4 offen offset:128 lds
	s_add_i32 m0, s43, 0x10400
	s_nop 0
	buffer_load_dwordx4 v251, s[12:15], s4 offen lds
	s_add_i32 m0, s43, 0x12400
	s_nop 0
	buffer_load_dwordx4 v251, s[12:15], s4 offen offset:128 lds
	ds_read_b64_tr_b16 v[192:193], v179 offset:16640
	ds_read_b64_tr_b16 v[194:195], v179 offset:17152
	ds_read_b64_tr_b16 v[196:197], v179 offset:20800
	ds_read_b64_tr_b16 v[198:199], v179 offset:21312
	ds_read_b64_tr_b16 v[200:201], v179 offset:24960
	ds_read_b64_tr_b16 v[202:203], v179 offset:25472
	ds_read_b64_tr_b16 v[204:205], v179 offset:29120
	ds_read_b64_tr_b16 v[206:207], v179 offset:29632
	ds_read_b64_tr_b16 v[208:209], v179 offset:17664
	ds_read_b64_tr_b16 v[210:211], v179 offset:18176
	ds_read_b64_tr_b16 v[212:213], v179 offset:21824
	ds_read_b64_tr_b16 v[214:215], v179 offset:22336
	ds_read_b64_tr_b16 v[216:217], v179 offset:25984
	ds_read_b64_tr_b16 v[218:219], v179 offset:26496
	ds_read_b64_tr_b16 v[220:221], v179 offset:30144
	ds_read_b64_tr_b16 v[222:223], v179 offset:30656
	v_exp_f32_e32 v240, v112
	v_exp_f32_e32 v241, v113
	v_exp_f32_e32 v242, v114
	v_exp_f32_e32 v243, v115
	v_exp_f32_e32 v244, v116
	v_exp_f32_e32 v245, v117
	v_add_f32_e32 v145, v240, v241
	v_cvt_pk_bf16_f32 v224, v240, v241
	v_exp_f32_e32 v246, v118
	v_exp_f32_e32 v247, v119
	v_add_f32_e32 v145, v145, v242
	v_add_f32_e32 v145, v145, v243
	v_cvt_pk_bf16_f32 v225, v242, v243
	v_exp_f32_e32 v240, v120
	v_exp_f32_e32 v241, v121
	v_add_f32_e32 v145, v145, v244
	v_add_f32_e32 v145, v145, v245
	v_cvt_pk_bf16_f32 v226, v244, v245
	v_exp_f32_e32 v242, v122
	v_exp_f32_e32 v243, v123
	v_add_f32_e32 v145, v145, v246
	v_add_f32_e32 v145, v145, v247
	v_cvt_pk_bf16_f32 v227, v246, v247
	v_exp_f32_e32 v244, v124
	v_exp_f32_e32 v245, v125
	v_add_f32_e32 v145, v145, v240
	v_add_f32_e32 v145, v145, v241
	v_cvt_pk_bf16_f32 v228, v240, v241
	v_exp_f32_e32 v246, v126
	v_exp_f32_e32 v247, v127
	v_add_f32_e32 v145, v145, v242
	v_add_f32_e32 v145, v145, v243
	v_cvt_pk_bf16_f32 v229, v242, v243
	v_add_f32_e32 v145, v145, v244
	v_add_f32_e32 v145, v145, v245
	v_cvt_pk_bf16_f32 v230, v244, v245
	v_add_f32_e32 v145, v145, v246
	v_add_f32_e32 v248, v145, v247
	v_cvt_pk_bf16_f32 v231, v246, v247
.Lb_loop:
	s_waitcnt lgkmcnt(0)
	v_mfma_f32_32x32x16_bf16 v[32:47], v[192:195], v[224:227], v[32:47]
	ds_read_b128 v[96:99], v146 offset:33280
	ds_read_b128 v[100:103], v147 offset:33280
	ds_read_b128 v[104:107], v148 offset:33280
	ds_read_b128 v[108:111], v149 offset:33280
	s_add_i32 s0, s50, 0xffff8000
	s_and_b32 s0, s0, 0x1f8000
	s_lshl_b32 s4, s0, 1
	s_add_i32 m0, s41, 0x18600
	s_nop 0
	buffer_load_dwordx4 v250, s[8:11], s4 offen lds
	s_add_i32 m0, s41, 0x1a600
	s_nop 0
	buffer_load_dwordx4 v250, s[8:11], s4 offen offset:128 lds
	ds_read_b64_tr_b16 v[192:193], v179 offset:18688
	ds_read_b64_tr_b16 v[194:195], v179 offset:19200
	v_exp_f32_e32 v240, v80
	v_exp_f32_e32 v241, v81
	v_mfma_f32_32x32x16_bf16 v[48:63], v[196:199], v[224:227], v[48:63]
	ds_read_b64_tr_b16 v[196:197], v179 offset:22848
	ds_read_b64_tr_b16 v[198:199], v179 offset:23360
	s_add_i32 m0, s43, 0x18600
	s_nop 0
	buffer_load_dwordx4 v251, s[12:15], s4 offen lds
	s_add_i32 m0, s43, 0x1a600
	s_nop 0
	buffer_load_dwordx4 v251, s[12:15], s4 offen offset:128 lds
	v_exp_f32_e32 v242, v82
	v_exp_f32_e32 v243, v83
	v_exp_f32_e32 v244, v84
	v_mfma_f32_32x32x16_bf16 v[16:31], v[200:203], v[224:227], v[16:31]
	ds_read_b64_tr_b16 v[200:201], v179 offset:27008
	ds_read_b64_tr_b16 v[202:203], v179 offset:27520
	v_exp_f32_e32 v245, v85
	v_add_f32_e32 v145, v240, v241
	v_cvt_pk_bf16_f32 v232, v240, v241
	v_mfma_f32_32x32x16_bf16 v[0:15], v[204:207], v[224:227], v[0:15]
	ds_read_b64_tr_b16 v[204:205], v179 offset:31168
	ds_read_b64_tr_b16 v[206:207], v179 offset:31680
	v_exp_f32_e32 v246, v86
	v_exp_f32_e32 v247, v87
	v_add_f32_e32 v145, v145, v242
	s_waitcnt lgkmcnt(8)
	v_mfma_f32_32x32x16_bf16 v[112:127], v[96:99], v[128:131], v[64:79]
	ds_read_b128 v[96:99], v146 offset:37376
	v_add_f32_e32 v145, v145, v243
	v_cvt_pk_bf16_f32 v233, v242, v243
	v_exp_f32_e32 v240, v88
	v_exp_f32_e32 v241, v89
	v_mfma_f32_32x32x16_bf16 v[112:127], v[100:103], v[132:135], v[112:127]
	ds_read_b128 v[100:103], v147 offset:37376
	v_add_f32_e32 v145, v145, v244
	v_add_f32_e32 v145, v145, v245
	v_cvt_pk_bf16_f32 v234, v244, v245
	v_exp_f32_e32 v242, v90
	v_mfma_f32_32x32x16_bf16 v[112:127], v[104:107], v[136:139], v[112:127]
	ds_read_b128 v[104:107], v148 offset:37376
	v_exp_f32_e32 v243, v91
	v_add_f32_e32 v145, v145, v246
	v_add_f32_e32 v145, v145, v247
	v_mfma_f32_32x32x16_bf16 v[112:127], v[108:111], v[140:143], v[112:127]
	ds_read_b128 v[108:111], v149 offset:37376
	v_cvt_pk_bf16_f32 v235, v246, v247
	v_exp_f32_e32 v244, v92
	v_exp_f32_e32 v245, v93
	v_mfma_f32_32x32x16_bf16 v[32:47], v[208:211], v[228:231], v[32:47]
	ds_read_b64_tr_b16 v[208:209], v179 offset:19712
	ds_read_b64_tr_b16 v[210:211], v179 offset:20224
	v_add_f32_e32 v145, v145, v240
	v_add_f32_e32 v145, v145, v241
	v_cvt_pk_bf16_f32 v236, v240, v241
	v_exp_f32_e32 v246, v94
	v_mfma_f32_32x32x16_bf16 v[48:63], v[212:215], v[228:231], v[48:63]
	ds_read_b64_tr_b16 v[212:213], v179 offset:23872
	ds_read_b64_tr_b16 v[214:215], v179 offset:24384
	v_exp_f32_e32 v247, v95
	v_add_f32_e32 v145, v145, v242
	v_add_f32_e32 v145, v145, v243
	v_mfma_f32_32x32x16_bf16 v[16:31], v[216:219], v[228:231], v[16:31]
	ds_read_b64_tr_b16 v[216:217], v179 offset:28032
	ds_read_b64_tr_b16 v[218:219], v179 offset:28544
	v_cvt_pk_bf16_f32 v237, v242, v243
	v_add_f32_e32 v145, v145, v244
	v_add_f32_e32 v145, v145, v245
	v_cvt_pk_bf16_f32 v238, v244, v245
	v_add_f32_e32 v145, v145, v246
	v_mfma_f32_32x32x16_bf16 v[0:15], v[220:223], v[228:231], v[0:15]
	ds_read_b64_tr_b16 v[220:221], v179 offset:32192
	ds_read_b64_tr_b16 v[222:223], v179 offset:32704
	v_add_f32_e32 v249, v145, v247
	v_cvt_pk_bf16_f32 v239, v246, v247
	v_add_f32_e32 v249, v248, v249
	v_cmp_lt_f32_e32 vcc, s3, v249
	v_add_f32_e32 v191, v191, v249
	s_waitcnt lgkmcnt(8)
	v_mfma_f32_32x32x16_bf16 v[80:95], v[96:99], v[128:131], v[64:79]
	v_exp_f32_e32 v240, v112
	v_exp_f32_e32 v241, v113
	v_mfma_f32_32x32x16_bf16 v[80:95], v[100:103], v[132:135], v[80:95]
	v_exp_f32_e32 v242, v114
	v_exp_f32_e32 v243, v115
	v_exp_f32_e32 v244, v116
	v_mfma_f32_32x32x16_bf16 v[80:95], v[104:107], v[136:139], v[80:95]
	v_exp_f32_e32 v245, v117
	v_add_f32_e32 v145, v240, v241
	v_cvt_pk_bf16_f32 v224, v240, v241
	v_mfma_f32_32x32x16_bf16 v[80:95], v[108:111], v[140:143], v[80:95]
	v_exp_f32_e32 v246, v118
	v_exp_f32_e32 v247, v119
	v_mfma_f32_32x32x16_bf16 v[32:47], v[192:195], v[232:235], v[32:47]
	ds_read_b64_tr_b16 v[192:193], v180 offset:0
	ds_read_b64_tr_b16 v[194:195], v180 offset:512
	v_add_f32_e32 v145, v145, v242
	v_add_f32_e32 v145, v145, v243
	v_cvt_pk_bf16_f32 v225, v242, v243
	v_exp_f32_e32 v240, v120
	v_mfma_f32_32x32x16_bf16 v[48:63], v[196:199], v[232:235], v[48:63]
	ds_read_b64_tr_b16 v[196:197], v180 offset:4160
	ds_read_b64_tr_b16 v[198:199], v180 offset:4672
	v_exp_f32_e32 v241, v121
	v_add_f32_e32 v145, v145, v244
	v_add_f32_e32 v145, v145, v245
	v_cvt_pk_bf16_f32 v226, v244, v245
	v_mfma_f32_32x32x16_bf16 v[16:31], v[200:203], v[232:235], v[16:31]
	ds_read_b64_tr_b16 v[200:201], v180 offset:8320
	ds_read_b64_tr_b16 v[202:203], v180 offset:8832
	v_exp_f32_e32 v242, v122
	v_exp_f32_e32 v243, v123
	v_mfma_f32_32x32x16_bf16 v[0:15], v[204:207], v[232:235], v[0:15]
	ds_read_b64_tr_b16 v[204:205], v180 offset:12480
	ds_read_b64_tr_b16 v[206:207], v180 offset:12992
	v_add_f32_e32 v145, v145, v246
	v_add_f32_e32 v145, v145, v247
	v_cvt_pk_bf16_f32 v227, v246, v247
	v_exp_f32_e32 v244, v124
	s_waitcnt lgkmcnt(8)
	v_mfma_f32_32x32x16_bf16 v[32:47], v[208:211], v[236:239], v[32:47]
	ds_read_b64_tr_b16 v[208:209], v180 offset:1024
	ds_read_b64_tr_b16 v[210:211], v180 offset:1536
	v_exp_f32_e32 v245, v125
	v_add_f32_e32 v145, v145, v240
	v_add_f32_e32 v145, v145, v241
	v_mfma_f32_32x32x16_bf16 v[48:63], v[212:215], v[236:239], v[48:63]
	ds_read_b64_tr_b16 v[212:213], v180 offset:5184
	ds_read_b64_tr_b16 v[214:215], v180 offset:5696
	v_cvt_pk_bf16_f32 v228, v240, v241
	v_exp_f32_e32 v246, v126
	v_exp_f32_e32 v247, v127
	v_mfma_f32_32x32x16_bf16 v[16:31], v[216:219], v[236:239], v[16:31]
	ds_read_b64_tr_b16 v[216:217], v180 offset:9344
	ds_read_b64_tr_b16 v[218:219], v180 offset:9856
	v_add_f32_e32 v145, v145, v242
	v_add_f32_e32 v145, v145, v243
	v_cvt_pk_bf16_f32 v229, v242, v243
	v_add_f32_e32 v145, v145, v244
	v_mfma_f32_32x32x16_bf16 v[0:15], v[220:223], v[236:239], v[0:15]
	ds_read_b64_tr_b16 v[220:221], v180 offset:13504
	ds_read_b64_tr_b16 v[222:223], v180 offset:14016
	v_add_f32_e32 v145, v145, v245
	v_cvt_pk_bf16_f32 v230, v244, v245
	v_add_f32_e32 v145, v145, v246
	v_add_f32_e32 v248, v145, v247
	v_cvt_pk_bf16_f32 v231, v246, v247
	s_cbranch_vccz .Lb_cont0
	s_branch .Lb_rare0
.Lb_cont0:
	s_waitcnt vmcnt(4)
	s_barrier
	s_waitcnt lgkmcnt(0)
	v_mfma_f32_32x32x16_bf16 v[32:47], v[192:195], v[224:227], v[32:47]
	ds_read_b128 v[96:99], v150 offset:0
	ds_read_b128 v[100:103], v151 offset:0
	ds_read_b128 v[104:107], v152 offset:0
	ds_read_b128 v[108:111], v153 offset:0
	s_cmp_gt_u32 s6, 59
	s_cbranch_scc1 .Lb_nodma_k1
	s_and_b32 s0, s50, 0x1f8000
	s_lshl_b32 s4, s0, 1
	s_add_i32 m0, s41, 0x0
	s_nop 0
	buffer_load_dwordx4 v250, s[8:11], s4 offen lds
	s_add_i32 m0, s41, 0x2000
	s_nop 0
	buffer_load_dwordx4 v250, s[8:11], s4 offen offset:128 lds
	s_branch .Lb_dmaok_k1

.Lb_dmaok_k1:
	ds_read_b64_tr_b16 v[192:193], v180 offset:2048
	ds_read_b64_tr_b16 v[194:195], v180 offset:2560
	v_exp_f32_e32 v240, v80
	v_exp_f32_e32 v241, v81
	v_mfma_f32_32x32x16_bf16 v[48:63], v[196:199], v[224:227], v[48:63]
	ds_read_b64_tr_b16 v[196:197], v180 offset:6208
	ds_read_b64_tr_b16 v[198:199], v180 offset:6720
	s_cmp_gt_u32 s6, 59
	s_cbranch_scc1 .Lb_nodma_v1
	s_add_i32 m0, s43, 0x0
	s_nop 0
	buffer_load_dwordx4 v251, s[12:15], s4 offen lds
	s_add_i32 m0, s43, 0x2000
	s_nop 0
	buffer_load_dwordx4 v251, s[12:15], s4 offen offset:128 lds
.Lb_nodma_v1:
	v_exp_f32_e32 v242, v82
	v_exp_f32_e32 v243, v83
	v_exp_f32_e32 v244, v84
	v_mfma_f32_32x32x16_bf16 v[16:31], v[200:203], v[224:227], v[16:31]
	ds_read_b64_tr_b16 v[200:201], v180 offset:10368
	ds_read_b64_tr_b16 v[202:203], v180 offset:10880
	v_exp_f32_e32 v245, v85
	v_add_f32_e32 v145, v240, v241
	v_cvt_pk_bf16_f32 v232, v240, v241
	v_mfma_f32_32x32x16_bf16 v[0:15], v[204:207], v[224:227], v[0:15]
	ds_read_b64_tr_b16 v[204:205], v180 offset:14528
	ds_read_b64_tr_b16 v[206:207], v180 offset:15040
	v_exp_f32_e32 v246, v86
	v_exp_f32_e32 v247, v87
	v_add_f32_e32 v145, v145, v242
	s_waitcnt lgkmcnt(8)
	v_mfma_f32_32x32x16_bf16 v[112:127], v[96:99], v[128:131], v[64:79]
	ds_read_b128 v[96:99], v150 offset:4096
	v_add_f32_e32 v145, v145, v243
	v_cvt_pk_bf16_f32 v233, v242, v243
	v_exp_f32_e32 v240, v88
	v_exp_f32_e32 v241, v89
	v_mfma_f32_32x32x16_bf16 v[112:127], v[100:103], v[132:135], v[112:127]
	ds_read_b128 v[100:103], v151 offset:4096
	v_add_f32_e32 v145, v145, v244
	v_add_f32_e32 v145, v145, v245
	v_cvt_pk_bf16_f32 v234, v244, v245
	v_exp_f32_e32 v242, v90
	v_mfma_f32_32x32x16_bf16 v[112:127], v[104:107], v[136:139], v[112:127]
	ds_read_b128 v[104:107], v152 offset:4096
	v_exp_f32_e32 v243, v91
	v_add_f32_e32 v145, v145, v246
	v_add_f32_e32 v145, v145, v247
	v_mfma_f32_32x32x16_bf16 v[112:127], v[108:111], v[140:143], v[112:127]
	ds_read_b128 v[108:111], v153 offset:4096
	v_cvt_pk_bf16_f32 v235, v246, v247
	v_exp_f32_e32 v244, v92
	v_exp_f32_e32 v245, v93
	v_mfma_f32_32x32x16_bf16 v[32:47], v[208:211], v[228:231], v[32:47]
	ds_read_b64_tr_b16 v[208:209], v180 offset:3072
	ds_read_b64_tr_b16 v[210:211], v180 offset:3584
	v_add_f32_e32 v145, v145, v240
	v_add_f32_e32 v145, v145, v241
	v_cvt_pk_bf16_f32 v236, v240, v241
	v_exp_f32_e32 v246, v94
	v_mfma_f32_32x32x16_bf16 v[48:63], v[212:215], v[228:231], v[48:63]
	ds_read_b64_tr_b16 v[212:213], v180 offset:7232
	ds_read_b64_tr_b16 v[214:215], v180 offset:7744
	v_exp_f32_e32 v247, v95
	v_add_f32_e32 v145, v145, v242
	v_add_f32_e32 v145, v145, v243
	v_mfma_f32_32x32x16_bf16 v[16:31], v[216:219], v[228:231], v[16:31]
	ds_read_b64_tr_b16 v[216:217], v180 offset:11392
	ds_read_b64_tr_b16 v[218:219], v180 offset:11904
	v_cvt_pk_bf16_f32 v237, v242, v243
	v_add_f32_e32 v145, v145, v244
	v_add_f32_e32 v145, v145, v245
	v_cvt_pk_bf16_f32 v238, v244, v245
	v_add_f32_e32 v145, v145, v246
	v_mfma_f32_32x32x16_bf16 v[0:15], v[220:223], v[228:231], v[0:15]
	ds_read_b64_tr_b16 v[220:221], v180 offset:15552
	ds_read_b64_tr_b16 v[222:223], v180 offset:16064
	v_add_f32_e32 v249, v145, v247
	v_cvt_pk_bf16_f32 v239, v246, v247
	v_add_f32_e32 v249, v248, v249
	v_cmp_lt_f32_e32 vcc, s3, v249
	v_add_f32_e32 v191, v191, v249
	s_waitcnt lgkmcnt(8)
	v_mfma_f32_32x32x16_bf16 v[80:95], v[96:99], v[128:131], v[64:79]
	v_exp_f32_e32 v240, v112
	v_exp_f32_e32 v241, v113
	v_mfma_f32_32x32x16_bf16 v[80:95], v[100:103], v[132:135], v[80:95]
	v_exp_f32_e32 v242, v114
	v_exp_f32_e32 v243, v115
	v_exp_f32_e32 v244, v116
	v_mfma_f32_32x32x16_bf16 v[80:95], v[104:107], v[136:139], v[80:95]
	v_exp_f32_e32 v245, v117
	v_add_f32_e32 v145, v240, v241
	v_cvt_pk_bf16_f32 v224, v240, v241
	v_mfma_f32_32x32x16_bf16 v[80:95], v[108:111], v[140:143], v[80:95]
	v_exp_f32_e32 v246, v118
	v_exp_f32_e32 v247, v119
	v_mfma_f32_32x32x16_bf16 v[32:47], v[192:195], v[232:235], v[32:47]
	ds_read_b64_tr_b16 v[192:193], v182 offset:0
	ds_read_b64_tr_b16 v[194:195], v182 offset:512
	v_add_f32_e32 v145, v145, v242
	v_add_f32_e32 v145, v145, v243
	v_cvt_pk_bf16_f32 v225, v242, v243
	v_exp_f32_e32 v240, v120
	v_mfma_f32_32x32x16_bf16 v[48:63], v[196:199], v[232:235], v[48:63]
	ds_read_b64_tr_b16 v[196:197], v182 offset:4160
	ds_read_b64_tr_b16 v[198:199], v182 offset:4672
	v_exp_f32_e32 v241, v121
	v_add_f32_e32 v145, v145, v244
	v_add_f32_e32 v145, v145, v245
	v_cvt_pk_bf16_f32 v226, v244, v245
	v_mfma_f32_32x32x16_bf16 v[16:31], v[200:203], v[232:235], v[16:31]
	ds_read_b64_tr_b16 v[200:201], v182 offset:8320
	ds_read_b64_tr_b16 v[202:203], v182 offset:8832
	v_exp_f32_e32 v242, v122
	v_exp_f32_e32 v243, v123
	v_mfma_f32_32x32x16_bf16 v[0:15], v[204:207], v[232:235], v[0:15]
	ds_read_b64_tr_b16 v[204:205], v182 offset:12480
	ds_read_b64_tr_b16 v[206:207], v182 offset:12992
	v_add_f32_e32 v145, v145, v246
	v_add_f32_e32 v145, v145, v247
	v_cvt_pk_bf16_f32 v227, v246, v247
	v_exp_f32_e32 v244, v124
	s_waitcnt lgkmcnt(8)
	v_mfma_f32_32x32x16_bf16 v[32:47], v[208:211], v[236:239], v[32:47]
	ds_read_b64_tr_b16 v[208:209], v182 offset:1024
	ds_read_b64_tr_b16 v[210:211], v182 offset:1536
	v_exp_f32_e32 v245, v125
	v_add_f32_e32 v145, v145, v240
	v_add_f32_e32 v145, v145, v241
	v_mfma_f32_32x32x16_bf16 v[48:63], v[212:215], v[236:239], v[48:63]
	ds_read_b64_tr_b16 v[212:213], v182 offset:5184
	ds_read_b64_tr_b16 v[214:215], v182 offset:5696
	v_cvt_pk_bf16_f32 v228, v240, v241
	v_exp_f32_e32 v246, v126
	v_exp_f32_e32 v247, v127
	v_mfma_f32_32x32x16_bf16 v[16:31], v[216:219], v[236:239], v[16:31]
	ds_read_b64_tr_b16 v[216:217], v182 offset:9344
	ds_read_b64_tr_b16 v[218:219], v182 offset:9856
	v_add_f32_e32 v145, v145, v242
	v_add_f32_e32 v145, v145, v243
	v_cvt_pk_bf16_f32 v229, v242, v243
	v_add_f32_e32 v145, v145, v244
	v_mfma_f32_32x32x16_bf16 v[0:15], v[220:223], v[236:239], v[0:15]
	ds_read_b64_tr_b16 v[220:221], v182 offset:13504
	ds_read_b64_tr_b16 v[222:223], v182 offset:14016
	v_add_f32_e32 v145, v145, v245
	v_cvt_pk_bf16_f32 v230, v244, v245
	v_add_f32_e32 v145, v145, v246
	v_add_f32_e32 v248, v145, v247
	v_cvt_pk_bf16_f32 v231, v246, v247
	s_cbranch_vccz .Lb_cont1
	s_branch .Lb_rare1
.Lb_cont1:
	s_waitcnt vmcnt(4)
	s_barrier
	s_waitcnt lgkmcnt(0)
	v_mfma_f32_32x32x16_bf16 v[32:47], v[192:195], v[224:227], v[32:47]
	ds_read_b128 v[96:99], v150 offset:33280
	ds_read_b128 v[100:103], v151 offset:33280
	ds_read_b128 v[104:107], v152 offset:33280
	ds_read_b128 v[108:111], v153 offset:33280
	s_cmp_gt_u32 s6, 59
	s_cbranch_scc1 .Lb_nodma_k2
	s_add_i32 s0, s50, 0x8000
	s_and_b32 s0, s0, 0x1f8000
	s_lshl_b32 s4, s0, 1
	s_add_i32 m0, s41, 0x8200
	s_nop 0
	buffer_load_dwordx4 v250, s[8:11], s4 offen lds
	s_add_i32 m0, s41, 0xa200
	s_nop 0
	buffer_load_dwordx4 v250, s[8:11], s4 offen offset:128 lds
	s_branch .Lb_dmaok_k2

.Lb_dmaok_k2:
	ds_read_b64_tr_b16 v[192:193], v182 offset:2048
	ds_read_b64_tr_b16 v[194:195], v182 offset:2560
	v_exp_f32_e32 v240, v80
	v_exp_f32_e32 v241, v81
	v_mfma_f32_32x32x16_bf16 v[48:63], v[196:199], v[224:227], v[48:63]
	ds_read_b64_tr_b16 v[196:197], v182 offset:6208
	ds_read_b64_tr_b16 v[198:199], v182 offset:6720
	s_cmp_gt_u32 s6, 59
	s_cbranch_scc1 .Lb_nodma_v2
	s_add_i32 m0, s43, 0x8200
	s_nop 0
	buffer_load_dwordx4 v251, s[12:15], s4 offen lds
	s_add_i32 m0, s43, 0xa200
	s_nop 0
	buffer_load_dwordx4 v251, s[12:15], s4 offen offset:128 lds
.Lb_nodma_v2:
	v_exp_f32_e32 v242, v82
	v_exp_f32_e32 v243, v83
	v_exp_f32_e32 v244, v84
	v_mfma_f32_32x32x16_bf16 v[16:31], v[200:203], v[224:227], v[16:31]
	ds_read_b64_tr_b16 v[200:201], v182 offset:10368
	ds_read_b64_tr_b16 v[202:203], v182 offset:10880
	v_exp_f32_e32 v245, v85
	v_add_f32_e32 v145, v240, v241
	v_cvt_pk_bf16_f32 v232, v240, v241
	v_mfma_f32_32x32x16_bf16 v[0:15], v[204:207], v[224:227], v[0:15]
	ds_read_b64_tr_b16 v[204:205], v182 offset:14528
	ds_read_b64_tr_b16 v[206:207], v182 offset:15040
	v_exp_f32_e32 v246, v86
	v_exp_f32_e32 v247, v87
	v_add_f32_e32 v145, v145, v242
	s_waitcnt lgkmcnt(8)
	v_mfma_f32_32x32x16_bf16 v[112:127], v[96:99], v[128:131], v[64:79]
	ds_read_b128 v[96:99], v150 offset:37376
	v_add_f32_e32 v145, v145, v243
	v_cvt_pk_bf16_f32 v233, v242, v243
	v_exp_f32_e32 v240, v88
	v_exp_f32_e32 v241, v89
	v_mfma_f32_32x32x16_bf16 v[112:127], v[100:103], v[132:135], v[112:127]
	ds_read_b128 v[100:103], v151 offset:37376
	v_add_f32_e32 v145, v145, v244
	v_add_f32_e32 v145, v145, v245
	v_cvt_pk_bf16_f32 v234, v244, v245
	v_exp_f32_e32 v242, v90
	v_mfma_f32_32x32x16_bf16 v[112:127], v[104:107], v[136:139], v[112:127]
	ds_read_b128 v[104:107], v152 offset:37376
	v_exp_f32_e32 v243, v91
	v_add_f32_e32 v145, v145, v246
	v_add_f32_e32 v145, v145, v247
	v_mfma_f32_32x32x16_bf16 v[112:127], v[108:111], v[140:143], v[112:127]
	ds_read_b128 v[108:111], v153 offset:37376
	v_cvt_pk_bf16_f32 v235, v246, v247
	v_exp_f32_e32 v244, v92
	v_exp_f32_e32 v245, v93
	v_mfma_f32_32x32x16_bf16 v[32:47], v[208:211], v[228:231], v[32:47]
	ds_read_b64_tr_b16 v[208:209], v182 offset:3072
	ds_read_b64_tr_b16 v[210:211], v182 offset:3584
	v_add_f32_e32 v145, v145, v240
	v_add_f32_e32 v145, v145, v241
	v_cvt_pk_bf16_f32 v236, v240, v241
	v_exp_f32_e32 v246, v94
	v_mfma_f32_32x32x16_bf16 v[48:63], v[212:215], v[228:231], v[48:63]
	ds_read_b64_tr_b16 v[212:213], v182 offset:7232
	ds_read_b64_tr_b16 v[214:215], v182 offset:7744
	v_exp_f32_e32 v247, v95
	v_add_f32_e32 v145, v145, v242
	v_add_f32_e32 v145, v145, v243
	v_mfma_f32_32x32x16_bf16 v[16:31], v[216:219], v[228:231], v[16:31]
	ds_read_b64_tr_b16 v[216:217], v182 offset:11392
	ds_read_b64_tr_b16 v[218:219], v182 offset:11904
	v_cvt_pk_bf16_f32 v237, v242, v243
	v_add_f32_e32 v145, v145, v244
	v_add_f32_e32 v145, v145, v245
	v_cvt_pk_bf16_f32 v238, v244, v245
	v_add_f32_e32 v145, v145, v246
	v_mfma_f32_32x32x16_bf16 v[0:15], v[220:223], v[228:231], v[0:15]
	ds_read_b64_tr_b16 v[220:221], v182 offset:15552
	ds_read_b64_tr_b16 v[222:223], v182 offset:16064
	v_add_f32_e32 v249, v145, v247
	v_cvt_pk_bf16_f32 v239, v246, v247
	v_add_f32_e32 v249, v248, v249
	v_cmp_lt_f32_e32 vcc, s3, v249
	v_add_f32_e32 v191, v191, v249
	s_waitcnt lgkmcnt(8)
	v_mfma_f32_32x32x16_bf16 v[80:95], v[96:99], v[128:131], v[64:79]
	v_exp_f32_e32 v240, v112
	v_exp_f32_e32 v241, v113
	v_mfma_f32_32x32x16_bf16 v[80:95], v[100:103], v[132:135], v[80:95]
	v_exp_f32_e32 v242, v114
	v_exp_f32_e32 v243, v115
	v_exp_f32_e32 v244, v116
	v_mfma_f32_32x32x16_bf16 v[80:95], v[104:107], v[136:139], v[80:95]
	v_exp_f32_e32 v245, v117
	v_add_f32_e32 v145, v240, v241
	v_cvt_pk_bf16_f32 v224, v240, v241
	v_mfma_f32_32x32x16_bf16 v[80:95], v[108:111], v[140:143], v[80:95]
	v_exp_f32_e32 v246, v118
	v_exp_f32_e32 v247, v119
	v_mfma_f32_32x32x16_bf16 v[32:47], v[192:195], v[232:235], v[32:47]
	ds_read_b64_tr_b16 v[192:193], v182 offset:33280
	ds_read_b64_tr_b16 v[194:195], v182 offset:33792
	v_add_f32_e32 v145, v145, v242
	v_add_f32_e32 v145, v145, v243
	v_cvt_pk_bf16_f32 v225, v242, v243
	v_exp_f32_e32 v240, v120
	v_mfma_f32_32x32x16_bf16 v[48:63], v[196:199], v[232:235], v[48:63]
	ds_read_b64_tr_b16 v[196:197], v182 offset:37440
	ds_read_b64_tr_b16 v[198:199], v182 offset:37952
	v_exp_f32_e32 v241, v121
	v_add_f32_e32 v145, v145, v244
	v_add_f32_e32 v145, v145, v245
	v_cvt_pk_bf16_f32 v226, v244, v245
	v_mfma_f32_32x32x16_bf16 v[16:31], v[200:203], v[232:235], v[16:31]
	ds_read_b64_tr_b16 v[200:201], v182 offset:41600
	ds_read_b64_tr_b16 v[202:203], v182 offset:42112
	v_exp_f32_e32 v242, v122
	v_exp_f32_e32 v243, v123
	v_mfma_f32_32x32x16_bf16 v[0:15], v[204:207], v[232:235], v[0:15]
	ds_read_b64_tr_b16 v[204:205], v182 offset:45760
	ds_read_b64_tr_b16 v[206:207], v182 offset:46272
	v_add_f32_e32 v145, v145, v246
	v_add_f32_e32 v145, v145, v247
	v_cvt_pk_bf16_f32 v227, v246, v247
	v_exp_f32_e32 v244, v124
	s_waitcnt lgkmcnt(8)
	v_mfma_f32_32x32x16_bf16 v[32:47], v[208:211], v[236:239], v[32:47]
	ds_read_b64_tr_b16 v[208:209], v182 offset:34304
	ds_read_b64_tr_b16 v[210:211], v182 offset:34816
	v_exp_f32_e32 v245, v125
	v_add_f32_e32 v145, v145, v240
	v_add_f32_e32 v145, v145, v241
	v_mfma_f32_32x32x16_bf16 v[48:63], v[212:215], v[236:239], v[48:63]
	ds_read_b64_tr_b16 v[212:213], v182 offset:38464
	ds_read_b64_tr_b16 v[214:215], v182 offset:38976
	v_cvt_pk_bf16_f32 v228, v240, v241
	v_exp_f32_e32 v246, v126
	v_exp_f32_e32 v247, v127
	v_mfma_f32_32x32x16_bf16 v[16:31], v[216:219], v[236:239], v[16:31]
	ds_read_b64_tr_b16 v[216:217], v182 offset:42624
	ds_read_b64_tr_b16 v[218:219], v182 offset:43136
	v_add_f32_e32 v145, v145, v242
	v_add_f32_e32 v145, v145, v243
	v_cvt_pk_bf16_f32 v229, v242, v243
	v_add_f32_e32 v145, v145, v244
	v_mfma_f32_32x32x16_bf16 v[0:15], v[220:223], v[236:239], v[0:15]
	ds_read_b64_tr_b16 v[220:221], v182 offset:46784
	ds_read_b64_tr_b16 v[222:223], v182 offset:47296
	v_add_f32_e32 v145, v145, v245
	v_cvt_pk_bf16_f32 v230, v244, v245
	v_add_f32_e32 v145, v145, v246
	v_add_f32_e32 v248, v145, v247
	v_cvt_pk_bf16_f32 v231, v246, v247
	s_cbranch_vccz .Lb_cont2
	s_branch .Lb_rare2
; __device__ __forceinline__ void attnB_unit(LAS unsigned char* lds, const unsigned char* ws, int unit, float lam, const float* subln_g) {
;     ...
;     for (int t3 = 0; t3 < NT - 1; t3 += 3) {
;         B_ITER(t3, 0, BBUF, 2 * BBUF);
;         B_ITER(t3 + 1, BBUF, 2 * BBUF, 0);
;         B_ITER(t3 + 2, 2 * BBUF, 0, BBUF);
;     }
;     B_ITER(NT - 1, 0, BBUF, 2 * BBUF);
.Lb_cont2:
	s_waitcnt vmcnt(4)
	s_barrier
	s_cmp_gt_u32 s6, 59
	s_cbranch_scc1 .Lb_final
	s_waitcnt lgkmcnt(0)
	v_mfma_f32_32x32x16_bf16 v[32:47], v[192:195], v[224:227], v[32:47]
	ds_read_b128 v[96:99], v146 offset:0
	ds_read_b128 v[100:103], v147 offset:0
	ds_read_b128 v[104:107], v148 offset:0
	ds_read_b128 v[108:111], v149 offset:0
	s_add_i32 s0, s50, 0x10000
	s_and_b32 s0, s0, 0x1f8000
	s_lshl_b32 s4, s0, 1
	s_add_i32 m0, s41, 0x10400
	s_nop 0
	buffer_load_dwordx4 v250, s[8:11], s4 offen lds
	s_add_i32 m0, s41, 0x12400
	s_nop 0
	buffer_load_dwordx4 v250, s[8:11], s4 offen offset:128 lds
	ds_read_b64_tr_b16 v[192:193], v182 offset:35328
	ds_read_b64_tr_b16 v[194:195], v182 offset:35840
	v_exp_f32_e32 v240, v80
	v_exp_f32_e32 v241, v81
	v_mfma_f32_32x32x16_bf16 v[48:63], v[196:199], v[224:227], v[48:63]
	ds_read_b64_tr_b16 v[196:197], v182 offset:39488
	ds_read_b64_tr_b16 v[198:199], v182 offset:40000
	s_add_i32 m0, s43, 0x10400
	s_nop 0
	buffer_load_dwordx4 v251, s[12:15], s4 offen lds
	s_add_i32 m0, s43, 0x12400
	s_nop 0
	buffer_load_dwordx4 v251, s[12:15], s4 offen offset:128 lds
	v_exp_f32_e32 v242, v82
	v_exp_f32_e32 v243, v83
	v_exp_f32_e32 v244, v84
	v_mfma_f32_32x32x16_bf16 v[16:31], v[200:203], v[224:227], v[16:31]
	ds_read_b64_tr_b16 v[200:201], v182 offset:43648
	ds_read_b64_tr_b16 v[202:203], v182 offset:44160
	v_exp_f32_e32 v245, v85
	v_add_f32_e32 v145, v240, v241
	v_cvt_pk_bf16_f32 v232, v240, v241
	v_mfma_f32_32x32x16_bf16 v[0:15], v[204:207], v[224:227], v[0:15]
	ds_read_b64_tr_b16 v[204:205], v182 offset:47808
	ds_read_b64_tr_b16 v[206:207], v182 offset:48320
	v_exp_f32_e32 v246, v86
	v_exp_f32_e32 v247, v87
	v_add_f32_e32 v145, v145, v242
	s_waitcnt lgkmcnt(8)
	v_mfma_f32_32x32x16_bf16 v[112:127], v[96:99], v[128:131], v[64:79]
	ds_read_b128 v[96:99], v146 offset:4096
	v_add_f32_e32 v145, v145, v243
	v_cvt_pk_bf16_f32 v233, v242, v243
	v_exp_f32_e32 v240, v88
	v_exp_f32_e32 v241, v89
	v_mfma_f32_32x32x16_bf16 v[112:127], v[100:103], v[132:135], v[112:127]
	ds_read_b128 v[100:103], v147 offset:4096
	v_add_f32_e32 v145, v145, v244
	v_add_f32_e32 v145, v145, v245
	v_cvt_pk_bf16_f32 v234, v244, v245
	v_exp_f32_e32 v242, v90
	v_mfma_f32_32x32x16_bf16 v[112:127], v[104:107], v[136:139], v[112:127]
	ds_read_b128 v[104:107], v148 offset:4096
	v_exp_f32_e32 v243, v91
	v_add_f32_e32 v145, v145, v246
	v_add_f32_e32 v145, v145, v247
	v_mfma_f32_32x32x16_bf16 v[112:127], v[108:111], v[140:143], v[112:127]
	ds_read_b128 v[108:111], v149 offset:4096
	v_cvt_pk_bf16_f32 v235, v246, v247
	v_exp_f32_e32 v244, v92
	v_exp_f32_e32 v245, v93
	v_mfma_f32_32x32x16_bf16 v[32:47], v[208:211], v[228:231], v[32:47]
	ds_read_b64_tr_b16 v[208:209], v182 offset:36352
	ds_read_b64_tr_b16 v[210:211], v182 offset:36864
	v_add_f32_e32 v145, v145, v240
	v_add_f32_e32 v145, v145, v241
	v_cvt_pk_bf16_f32 v236, v240, v241
	v_exp_f32_e32 v246, v94
	v_mfma_f32_32x32x16_bf16 v[48:63], v[212:215], v[228:231], v[48:63]
	ds_read_b64_tr_b16 v[212:213], v182 offset:40512
	ds_read_b64_tr_b16 v[214:215], v182 offset:41024
	v_exp_f32_e32 v247, v95
	v_add_f32_e32 v145, v145, v242
	v_add_f32_e32 v145, v145, v243
	v_mfma_f32_32x32x16_bf16 v[16:31], v[216:219], v[228:231], v[16:31]
	ds_read_b64_tr_b16 v[216:217], v182 offset:44672
	ds_read_b64_tr_b16 v[218:219], v182 offset:45184
	v_cvt_pk_bf16_f32 v237, v242, v243
	v_add_f32_e32 v145, v145, v244
	v_add_f32_e32 v145, v145, v245
	v_cvt_pk_bf16_f32 v238, v244, v245
	v_add_f32_e32 v145, v145, v246
	v_mfma_f32_32x32x16_bf16 v[0:15], v[220:223], v[228:231], v[0:15]
	ds_read_b64_tr_b16 v[220:221], v182 offset:48832
	ds_read_b64_tr_b16 v[222:223], v182 offset:49344
	v_add_f32_e32 v249, v145, v247
	v_cvt_pk_bf16_f32 v239, v246, v247
	v_add_f32_e32 v249, v248, v249
	v_cmp_lt_f32_e32 vcc, s3, v249
	v_add_f32_e32 v191, v191, v249
	s_waitcnt lgkmcnt(8)
	v_mfma_f32_32x32x16_bf16 v[80:95], v[96:99], v[128:131], v[64:79]
	v_exp_f32_e32 v240, v112
	v_exp_f32_e32 v241, v113
	v_mfma_f32_32x32x16_bf16 v[80:95], v[100:103], v[132:135], v[80:95]
	v_exp_f32_e32 v242, v114
	v_exp_f32_e32 v243, v115
	v_exp_f32_e32 v244, v116
	v_mfma_f32_32x32x16_bf16 v[80:95], v[104:107], v[136:139], v[80:95]
	v_exp_f32_e32 v245, v117
	v_add_f32_e32 v145, v240, v241
	v_cvt_pk_bf16_f32 v224, v240, v241
	v_mfma_f32_32x32x16_bf16 v[80:95], v[108:111], v[140:143], v[80:95]
	v_exp_f32_e32 v246, v118
	v_exp_f32_e32 v247, v119
	v_mfma_f32_32x32x16_bf16 v[32:47], v[192:195], v[232:235], v[32:47]
	ds_read_b64_tr_b16 v[192:193], v179 offset:16640
	ds_read_b64_tr_b16 v[194:195], v179 offset:17152
	v_add_f32_e32 v145, v145, v242
	v_add_f32_e32 v145, v145, v243
	v_cvt_pk_bf16_f32 v225, v242, v243
	v_exp_f32_e32 v240, v120
	v_mfma_f32_32x32x16_bf16 v[48:63], v[196:199], v[232:235], v[48:63]
	ds_read_b64_tr_b16 v[196:197], v179 offset:20800
	ds_read_b64_tr_b16 v[198:199], v179 offset:21312
	v_exp_f32_e32 v241, v121
	v_add_f32_e32 v145, v145, v244
	v_add_f32_e32 v145, v145, v245
	v_cvt_pk_bf16_f32 v226, v244, v245
	v_mfma_f32_32x32x16_bf16 v[16:31], v[200:203], v[232:235], v[16:31]
	ds_read_b64_tr_b16 v[200:201], v179 offset:24960
	ds_read_b64_tr_b16 v[202:203], v179 offset:25472
	v_exp_f32_e32 v242, v122
	v_exp_f32_e32 v243, v123
	v_mfma_f32_32x32x16_bf16 v[0:15], v[204:207], v[232:235], v[0:15]
	ds_read_b64_tr_b16 v[204:205], v179 offset:29120
	ds_read_b64_tr_b16 v[206:207], v179 offset:29632
	v_add_f32_e32 v145, v145, v246
	v_add_f32_e32 v145, v145, v247
	v_cvt_pk_bf16_f32 v227, v246, v247
	v_exp_f32_e32 v244, v124
	s_waitcnt lgkmcnt(8)
	v_mfma_f32_32x32x16_bf16 v[32:47], v[208:211], v[236:239], v[32:47]
	ds_read_b64_tr_b16 v[208:209], v179 offset:17664
	ds_read_b64_tr_b16 v[210:211], v179 offset:18176
	v_exp_f32_e32 v245, v125
	v_add_f32_e32 v145, v145, v240
	v_add_f32_e32 v145, v145, v241
	v_mfma_f32_32x32x16_bf16 v[48:63], v[212:215], v[236:239], v[48:63]
	ds_read_b64_tr_b16 v[212:213], v179 offset:21824
	ds_read_b64_tr_b16 v[214:215], v179 offset:22336
	v_cvt_pk_bf16_f32 v228, v240, v241
	v_exp_f32_e32 v246, v126
	v_exp_f32_e32 v247, v127
	v_mfma_f32_32x32x16_bf16 v[16:31], v[216:219], v[236:239], v[16:31]
	ds_read_b64_tr_b16 v[216:217], v179 offset:25984
	ds_read_b64_tr_b16 v[218:219], v179 offset:26496
	v_add_f32_e32 v145, v145, v242
	v_add_f32_e32 v145, v145, v243
	v_cvt_pk_bf16_f32 v229, v242, v243
	v_add_f32_e32 v145, v145, v244
	v_mfma_f32_32x32x16_bf16 v[0:15], v[220:223], v[236:239], v[0:15]
	ds_read_b64_tr_b16 v[220:221], v179 offset:30144
	ds_read_b64_tr_b16 v[222:223], v179 offset:30656
	v_add_f32_e32 v145, v145, v245
	v_cvt_pk_bf16_f32 v230, v244, v245
	v_add_f32_e32 v145, v145, v246
	v_add_f32_e32 v248, v145, v247
	v_cvt_pk_bf16_f32 v231, v246, v247
	s_cbranch_vccz .Lb_cont3
	s_branch .Lb_rare3
; __device__ __forceinline__ void attnB_unit(LAS unsigned char* lds, const unsigned char* ws, int unit, float lam, const float* subln_g) {
;     ...
;     for (int t3 = 0; t3 < NT - 1; t3 += 3) {
;         B_ITER(t3, 0, BBUF, 2 * BBUF);
;         B_ITER(t3 + 1, BBUF, 2 * BBUF, 0);
;         B_ITER(t3 + 2, 2 * BBUF, 0, BBUF);
;     }
;     B_ITER(NT - 1, 0, BBUF, 2 * BBUF);
.Lb_cont3:
	s_waitcnt vmcnt(4)
	s_add_i32 s6, s6, 4
	s_add_i32 s50, s50, 0x20000
	s_barrier
	s_branch .Lb_loop
.Lb_final:
	s_waitcnt lgkmcnt(0)
	v_mfma_f32_32x32x16_bf16 v[32:47], v[192:195], v[224:227], v[32:47]
	ds_read_b64_tr_b16 v[192:193], v182 offset:35328
	ds_read_b64_tr_b16 v[194:195], v182 offset:35840
	v_exp_f32_e32 v240, v80
	v_exp_f32_e32 v241, v81
	v_exp_f32_e32 v242, v82
	v_exp_f32_e32 v243, v83
	v_mfma_f32_32x32x16_bf16 v[48:63], v[196:199], v[224:227], v[48:63]
	ds_read_b64_tr_b16 v[196:197], v182 offset:39488
	ds_read_b64_tr_b16 v[198:199], v182 offset:40000
	v_exp_f32_e32 v244, v84
	v_exp_f32_e32 v245, v85
	v_add_f32_e32 v145, v240, v241
	v_cvt_pk_bf16_f32 v232, v240, v241
	v_mfma_f32_32x32x16_bf16 v[16:31], v[200:203], v[224:227], v[16:31]
	ds_read_b64_tr_b16 v[200:201], v182 offset:43648
	ds_read_b64_tr_b16 v[202:203], v182 offset:44160
	v_exp_f32_e32 v246, v86
	v_exp_f32_e32 v247, v87
	v_add_f32_e32 v145, v145, v242
	v_add_f32_e32 v145, v145, v243
	v_cvt_pk_bf16_f32 v233, v242, v243
	v_mfma_f32_32x32x16_bf16 v[0:15], v[204:207], v[224:227], v[0:15]
	ds_read_b64_tr_b16 v[204:205], v182 offset:47808
	ds_read_b64_tr_b16 v[206:207], v182 offset:48320
	v_exp_f32_e32 v240, v88
	v_exp_f32_e32 v241, v89
	v_add_f32_e32 v145, v145, v244
	v_add_f32_e32 v145, v145, v245
	v_cvt_pk_bf16_f32 v234, v244, v245
	v_mfma_f32_32x32x16_bf16 v[32:47], v[208:211], v[228:231], v[32:47]
	ds_read_b64_tr_b16 v[208:209], v182 offset:36352
	ds_read_b64_tr_b16 v[210:211], v182 offset:36864
	v_exp_f32_e32 v242, v90
	v_exp_f32_e32 v243, v91
	v_add_f32_e32 v145, v145, v246
	v_add_f32_e32 v145, v145, v247
	v_cvt_pk_bf16_f32 v235, v246, v247
	v_mfma_f32_32x32x16_bf16 v[48:63], v[212:215], v[228:231], v[48:63]
	ds_read_b64_tr_b16 v[212:213], v182 offset:40512
	ds_read_b64_tr_b16 v[214:215], v182 offset:41024
	v_exp_f32_e32 v244, v92
	v_exp_f32_e32 v245, v93
	v_add_f32_e32 v145, v145, v240
	v_add_f32_e32 v145, v145, v241
	v_cvt_pk_bf16_f32 v236, v240, v241
	v_mfma_f32_32x32x16_bf16 v[16:31], v[216:219], v[228:231], v[16:31]
	ds_read_b64_tr_b16 v[216:217], v182 offset:44672
	ds_read_b64_tr_b16 v[218:219], v182 offset:45184
	v_exp_f32_e32 v246, v94
	v_exp_f32_e32 v247, v95
	v_add_f32_e32 v145, v145, v242
	v_add_f32_e32 v145, v145, v243
	v_cvt_pk_bf16_f32 v237, v242, v243
	v_add_f32_e32 v145, v145, v244
	v_mfma_f32_32x32x16_bf16 v[0:15], v[220:223], v[228:231], v[0:15]
	ds_read_b64_tr_b16 v[220:221], v182 offset:48832
	ds_read_b64_tr_b16 v[222:223], v182 offset:49344
	v_add_f32_e32 v145, v145, v245
	v_cvt_pk_bf16_f32 v238, v244, v245
	v_add_f32_e32 v145, v145, v246
	v_add_f32_e32 v249, v145, v247
	v_cvt_pk_bf16_f32 v239, v246, v247
	v_add_f32_e32 v249, v248, v249
	v_add_f32_e32 v64, v191, v249
	s_waitcnt lgkmcnt(8)
	v_mfma_f32_32x32x16_bf16 v[32:47], v[192:195], v[232:235], v[32:47]
	v_mfma_f32_32x32x16_bf16 v[48:63], v[196:199], v[232:235], v[48:63]
	v_mfma_f32_32x32x16_bf16 v[16:31], v[200:203], v[232:235], v[16:31]
	v_mfma_f32_32x32x16_bf16 v[0:15], v[204:207], v[232:235], v[0:15]
	s_waitcnt lgkmcnt(0)
	v_mfma_f32_32x32x16_bf16 v[32:47], v[208:211], v[236:239], v[32:47]
	v_mfma_f32_32x32x16_bf16 v[48:63], v[212:215], v[236:239], v[48:63]
	v_mfma_f32_32x32x16_bf16 v[16:31], v[216:219], v[236:239], v[16:31]
	v_mfma_f32_32x32x16_bf16 v[0:15], v[220:223], v[236:239], v[0:15]
	s_branch .LBB0_306

.Lb_rare3:
	ds_bpermute_b32 v240, v189, v249
	s_waitcnt lgkmcnt(0)
	v_add_f32_e32 v240, v249, v240
	v_log_f32_e32 v241, v240
	v_cmp_lt_f32_e32 vcc, s3, v240
	v_floor_f32_e32 v241, v241
	s_nop 0
	v_cndmask_b32_e32 v241, 0, v241, vcc
	v_exp_f32_e64 v240, -v241
	v_sub_f32_e32 v64, v64, v241
	v_sub_f32_e32 v65, v65, v241
	v_sub_f32_e32 v66, v66, v241
	v_sub_f32_e32 v67, v67, v241
	v_sub_f32_e32 v68, v68, v241
	v_sub_f32_e32 v69, v69, v241
	v_sub_f32_e32 v70, v70, v241
	v_sub_f32_e32 v71, v71, v241
	v_sub_f32_e32 v72, v72, v241
	v_sub_f32_e32 v73, v73, v241
	v_sub_f32_e32 v74, v74, v241
	v_sub_f32_e32 v75, v75, v241
	v_sub_f32_e32 v76, v76, v241
	v_sub_f32_e32 v77, v77, v241
	v_sub_f32_e32 v78, v78, v241
	v_sub_f32_e32 v79, v79, v241
	v_sub_f32_e32 v112, v112, v241
	v_sub_f32_e32 v113, v113, v241
	v_sub_f32_e32 v114, v114, v241
	v_sub_f32_e32 v115, v115, v241
	v_sub_f32_e32 v116, v116, v241
	v_sub_f32_e32 v117, v117, v241
	v_sub_f32_e32 v118, v118, v241
	v_sub_f32_e32 v119, v119, v241
	v_sub_f32_e32 v120, v120, v241
	v_sub_f32_e32 v121, v121, v241
	v_sub_f32_e32 v122, v122, v241
	v_sub_f32_e32 v123, v123, v241
	v_sub_f32_e32 v124, v124, v241
	v_sub_f32_e32 v125, v125, v241
	v_sub_f32_e32 v126, v126, v241
	v_sub_f32_e32 v127, v127, v241
	v_sub_f32_e32 v80, v80, v241
	v_sub_f32_e32 v81, v81, v241
	v_sub_f32_e32 v82, v82, v241
	v_sub_f32_e32 v83, v83, v241
	v_sub_f32_e32 v84, v84, v241
	v_sub_f32_e32 v85, v85, v241
	v_sub_f32_e32 v86, v86, v241
	v_sub_f32_e32 v87, v87, v241
	v_sub_f32_e32 v88, v88, v241
	v_sub_f32_e32 v89, v89, v241
	v_sub_f32_e32 v90, v90, v241
	v_sub_f32_e32 v91, v91, v241
	v_sub_f32_e32 v92, v92, v241
	v_sub_f32_e32 v93, v93, v241
	v_sub_f32_e32 v94, v94, v241
	v_sub_f32_e32 v95, v95, v241
	v_mul_f32_e32 v0, v0, v240
	v_mul_f32_e32 v1, v1, v240
	v_mul_f32_e32 v2, v2, v240
	v_mul_f32_e32 v3, v3, v240
	v_mul_f32_e32 v4, v4, v240
	v_mul_f32_e32 v5, v5, v240
	v_mul_f32_e32 v6, v6, v240
	v_mul_f32_e32 v7, v7, v240
	v_mul_f32_e32 v8, v8, v240
	v_mul_f32_e32 v9, v9, v240
	v_mul_f32_e32 v10, v10, v240
	v_mul_f32_e32 v11, v11, v240
	v_mul_f32_e32 v12, v12, v240
	v_mul_f32_e32 v13, v13, v240
	v_mul_f32_e32 v14, v14, v240
	v_mul_f32_e32 v15, v15, v240
	v_mul_f32_e32 v16, v16, v240
	v_mul_f32_e32 v17, v17, v240
	v_mul_f32_e32 v18, v18, v240
	v_mul_f32_e32 v19, v19, v240
	v_mul_f32_e32 v20, v20, v240
	v_mul_f32_e32 v21, v21, v240
	v_mul_f32_e32 v22, v22, v240
	v_mul_f32_e32 v23, v23, v240
	v_mul_f32_e32 v24, v24, v240
	v_mul_f32_e32 v25, v25, v240
	v_mul_f32_e32 v26, v26, v240
	v_mul_f32_e32 v27, v27, v240
	v_mul_f32_e32 v28, v28, v240
	v_mul_f32_e32 v29, v29, v240
	v_mul_f32_e32 v30, v30, v240
	v_mul_f32_e32 v31, v31, v240
	v_mul_f32_e32 v32, v32, v240
	v_mul_f32_e32 v33, v33, v240
	v_mul_f32_e32 v34, v34, v240
	v_mul_f32_e32 v35, v35, v240
	v_mul_f32_e32 v36, v36, v240
	v_mul_f32_e32 v37, v37, v240
	v_mul_f32_e32 v38, v38, v240
	v_mul_f32_e32 v39, v39, v240
	v_mul_f32_e32 v40, v40, v240
	v_mul_f32_e32 v41, v41, v240
	v_mul_f32_e32 v42, v42, v240
	v_mul_f32_e32 v43, v43, v240
	v_mul_f32_e32 v44, v44, v240
	v_mul_f32_e32 v45, v45, v240
	v_mul_f32_e32 v46, v46, v240
	v_mul_f32_e32 v47, v47, v240
	v_mul_f32_e32 v48, v48, v240
	v_mul_f32_e32 v49, v49, v240
	v_mul_f32_e32 v50, v50, v240
	v_mul_f32_e32 v51, v51, v240
	v_mul_f32_e32 v52, v52, v240
	v_mul_f32_e32 v53, v53, v240
	v_mul_f32_e32 v54, v54, v240
	v_mul_f32_e32 v55, v55, v240
	v_mul_f32_e32 v56, v56, v240
	v_mul_f32_e32 v57, v57, v240
	v_mul_f32_e32 v58, v58, v240
	v_mul_f32_e32 v59, v59, v240
	v_mul_f32_e32 v60, v60, v240
	v_mul_f32_e32 v61, v61, v240
	v_mul_f32_e32 v62, v62, v240
	v_mul_f32_e32 v63, v63, v240
	v_mul_f32_e32 v191, v191, v240
	v_exp_f32_e32 v240, v112
	v_exp_f32_e32 v241, v113
	v_exp_f32_e32 v242, v114
	v_exp_f32_e32 v243, v115
	v_exp_f32_e32 v244, v116
	v_exp_f32_e32 v245, v117
	v_add_f32_e32 v145, v240, v241
	v_cvt_pk_bf16_f32 v224, v240, v241
	v_exp_f32_e32 v246, v118
	v_exp_f32_e32 v247, v119
	v_add_f32_e32 v145, v145, v242
	v_add_f32_e32 v145, v145, v243
	v_cvt_pk_bf16_f32 v225, v242, v243
	v_exp_f32_e32 v240, v120
	v_exp_f32_e32 v241, v121
	v_add_f32_e32 v145, v145, v244
	v_add_f32_e32 v145, v145, v245
	v_cvt_pk_bf16_f32 v226, v244, v245
	v_exp_f32_e32 v242, v122
	v_exp_f32_e32 v243, v123
	v_add_f32_e32 v145, v145, v246
	v_add_f32_e32 v145, v145, v247
	v_cvt_pk_bf16_f32 v227, v246, v247
	v_exp_f32_e32 v244, v124
	v_exp_f32_e32 v245, v125
	v_add_f32_e32 v145, v145, v240
	v_add_f32_e32 v145, v145, v241
	v_cvt_pk_bf16_f32 v228, v240, v241
	v_exp_f32_e32 v246, v126
	v_exp_f32_e32 v247, v127
	v_add_f32_e32 v145, v145, v242
	v_add_f32_e32 v145, v145, v243
	v_cvt_pk_bf16_f32 v229, v242, v243
	v_add_f32_e32 v145, v145, v244
	v_add_f32_e32 v145, v145, v245
	v_cvt_pk_bf16_f32 v230, v244, v245
	v_add_f32_e32 v145, v145, v246
	v_add_f32_e32 v248, v145, v247
	v_cvt_pk_bf16_f32 v231, v246, v247
	s_branch .Lb_cont3
; #define LAS __attribute__((address_space(3)))
; __device__ __forceinline__ float xhalf(float v) { return __shfl_xor(v, 32); }
; __device__ __forceinline__ void attnB_unit(LAS unsigned char* lds, const unsigned char* ws, int unit, float lam, const float* subln_g) {
;     ...
;     l += xhalf(l);
;     const float rl = 1.0f / l;
;     LAS float* ex = (LAS float*)lds + w * 4096 + lane;
;     if (c == 1) {
; #pragma unroll
;         for (int db = 0; db < 4; ++db)
; #pragma unroll
;             for (int i = 0; i < 16; ++i) ex[(db * 16 + i) * 64] = o[db][i] * rl;
;     }
.LBB0_306:
	ds_bpermute_b32 v65, v189, v64
	s_waitcnt vmcnt(0)
	s_cmp_lg_u32 s40, 1
	s_waitcnt lgkmcnt(0)
	s_barrier
	v_add_f32_e32 v64, v64, v65
	v_div_scale_f32 v65, s[0:1], v64, v64, 1.0
	v_rcp_f32_e32 v66, v65
	v_div_scale_f32 v67, vcc, 1.0, v64, 1.0
	v_fma_f32 v68, -v65, v66, 1.0
	v_fmac_f32_e32 v66, v68, v66
	v_mul_f32_e32 v68, v67, v66
	v_fma_f32 v69, -v65, v68, v67
	v_fmac_f32_e32 v68, v69, v66
	v_fma_f32 v65, -v65, v68, v67
	v_div_fmas_f32 v65, v65, v66, v68
	v_div_fixup_f32 v72, v65, v64, 1.0
	v_lshl_add_u32 v64, s39, 14, v181
	s_cbranch_scc1 .LBB0_308
	v_mul_f32_e32 v65, v32, v72
	v_mul_f32_e32 v66, v33, v72
	ds_write2st64_b32 v64, v65, v66 offset1:1
	v_mul_f32_e32 v65, v34, v72
	v_mul_f32_e32 v66, v35, v72
	ds_write2st64_b32 v64, v65, v66 offset0:2 offset1:3
	v_mul_f32_e32 v65, v36, v72
	v_mul_f32_e32 v66, v37, v72
	ds_write2st64_b32 v64, v65, v66 offset0:4 offset1:5
	v_mul_f32_e32 v65, v38, v72
	v_mul_f32_e32 v66, v39, v72
	ds_write2st64_b32 v64, v65, v66 offset0:6 offset1:7
	v_mul_f32_e32 v65, v40, v72
	v_mul_f32_e32 v66, v41, v72
	ds_write2st64_b32 v64, v65, v66 offset0:8 offset1:9
	v_mul_f32_e32 v65, v42, v72
	v_mul_f32_e32 v66, v43, v72
	ds_write2st64_b32 v64, v65, v66 offset0:10 offset1:11
	v_mul_f32_e32 v65, v44, v72
	v_mul_f32_e32 v66, v45, v72
	ds_write2st64_b32 v64, v65, v66 offset0:12 offset1:13
	v_mul_f32_e32 v65, v46, v72
	v_mul_f32_e32 v66, v47, v72
	ds_write2st64_b32 v64, v65, v66 offset0:14 offset1:15
	v_mul_f32_e32 v65, v48, v72
	v_mul_f32_e32 v66, v49, v72
	ds_write2st64_b32 v64, v65, v66 offset0:16 offset1:17
	v_mul_f32_e32 v65, v50, v72
	v_mul_f32_e32 v66, v51, v72
	ds_write2st64_b32 v64, v65, v66 offset0:18 offset1:19
	v_mul_f32_e32 v65, v52, v72
	v_mul_f32_e32 v66, v53, v72
	ds_write2st64_b32 v64, v65, v66 offset0:20 offset1:21
	v_mul_f32_e32 v65, v54, v72
	v_mul_f32_e32 v66, v55, v72
	ds_write2st64_b32 v64, v65, v66 offset0:22 offset1:23
	v_mul_f32_e32 v65, v56, v72
	v_mul_f32_e32 v66, v57, v72
	ds_write2st64_b32 v64, v65, v66 offset0:24 offset1:25
	v_mul_f32_e32 v65, v58, v72
	v_mul_f32_e32 v66, v59, v72
	ds_write2st64_b32 v64, v65, v66 offset0:26 offset1:27
	v_mul_f32_e32 v65, v60, v72
	v_mul_f32_e32 v66, v61, v72
	ds_write2st64_b32 v64, v65, v66 offset0:28 offset1:29
	v_mul_f32_e32 v65, v62, v72
	v_mul_f32_e32 v66, v63, v72
	ds_write2st64_b32 v64, v65, v66 offset0:30 offset1:31
	v_mul_f32_e32 v65, v16, v72
	v_mul_f32_e32 v66, v17, v72
	ds_write2st64_b32 v64, v65, v66 offset0:32 offset1:33
	v_mul_f32_e32 v65, v18, v72
	v_mul_f32_e32 v66, v19, v72
	ds_write2st64_b32 v64, v65, v66 offset0:34 offset1:35
	v_mul_f32_e32 v65, v20, v72
	v_mul_f32_e32 v66, v21, v72
	ds_write2st64_b32 v64, v65, v66 offset0:36 offset1:37
	v_mul_f32_e32 v65, v22, v72
	v_mul_f32_e32 v66, v23, v72
	ds_write2st64_b32 v64, v65, v66 offset0:38 offset1:39
	v_mul_f32_e32 v65, v24, v72
	v_mul_f32_e32 v66, v25, v72
	ds_write2st64_b32 v64, v65, v66 offset0:40 offset1:41
	v_mul_f32_e32 v65, v26, v72
	v_mul_f32_e32 v66, v27, v72
	ds_write2st64_b32 v64, v65, v66 offset0:42 offset1:43
	v_mul_f32_e32 v65, v28, v72
	v_mul_f32_e32 v66, v29, v72
	ds_write2st64_b32 v64, v65, v66 offset0:44 offset1:45
	v_mul_f32_e32 v65, v30, v72
	v_mul_f32_e32 v66, v31, v72
	ds_write2st64_b32 v64, v65, v66 offset0:46 offset1:47
	v_mul_f32_e32 v65, v0, v72
	v_mul_f32_e32 v66, v1, v72
	ds_write2st64_b32 v64, v65, v66 offset0:48 offset1:49
	v_mul_f32_e32 v65, v2, v72
	v_mul_f32_e32 v66, v3, v72
	ds_write2st64_b32 v64, v65, v66 offset0:50 offset1:51
	v_mul_f32_e32 v65, v4, v72
	v_mul_f32_e32 v66, v5, v72
	ds_write2st64_b32 v64, v65, v66 offset0:52 offset1:53
	v_mul_f32_e32 v65, v6, v72
	v_mul_f32_e32 v66, v7, v72
	ds_write2st64_b32 v64, v65, v66 offset0:54 offset1:55
	v_mul_f32_e32 v65, v8, v72
	v_mul_f32_e32 v66, v9, v72
	ds_write2st64_b32 v64, v65, v66 offset0:56 offset1:57
	v_mul_f32_e32 v65, v10, v72
	v_mul_f32_e32 v66, v11, v72
	ds_write2st64_b32 v64, v65, v66 offset0:58 offset1:59
	v_mul_f32_e32 v65, v12, v72
	v_mul_f32_e32 v66, v13, v72
	ds_write2st64_b32 v64, v65, v66 offset0:60 offset1:61
	v_mul_f32_e32 v65, v14, v72
	v_mul_f32_e32 v66, v15, v72
	ds_write2st64_b32 v64, v65, v66 offset0:62 offset1:63
